# grid-barrier poll loops: s_sleep 3 instead of 1 between flag polls (less poll traffic against the last arrivers)
# baseline (speedup 1.0000x reference)
.Lfs_topspin_2:
	s_sleep 3
	global_load_dword v3, v1, s[6:7] sc1
	s_waitcnt vmcnt(0)
	v_readfirstlane_b32 s9, v3
	s_nop 3
	s_cmp_lt_u32 s9, 1
	s_cbranch_scc1 .Lfs_topspin_2

.Lfs_topspin_3:
	s_sleep 3
	global_load_dword v3, v1, s[6:7] sc1
	s_waitcnt vmcnt(0)
	v_readfirstlane_b32 s11, v3
	s_nop 3
	s_cmp_lt_u32 s11, 2
	s_cbranch_scc1 .Lfs_topspin_3

.Lfs_topspin_4:
	s_sleep 3
	global_load_dword v3, v1, s[8:9] sc1
	s_waitcnt vmcnt(0)
	v_readfirstlane_b32 s11, v3
	s_nop 3
	s_cmp_lt_u32 s11, 3
	s_cbranch_scc1 .Lfs_topspin_4

.Lfs_topspin_5:
	s_sleep 3
	global_load_dword v3, v1, s[8:9] sc1
	s_waitcnt vmcnt(0)
	v_readfirstlane_b32 s11, v3
	s_nop 3
	s_cmp_lt_u32 s11, 4
	s_cbranch_scc1 .Lfs_topspin_5

.Lfs_topspin_6:
	s_sleep 3
	global_load_dword v3, v1, s[6:7] sc1
	s_waitcnt vmcnt(0)
	v_readfirstlane_b32 s9, v3
	s_nop 3
	s_cmp_lt_u32 s9, 5
	s_cbranch_scc1 .Lfs_topspin_6

.Lfs_topspin_7:
	s_sleep 3
	global_load_dword v3, v1, s[6:7] sc1
	s_waitcnt vmcnt(0)
	v_readfirstlane_b32 s9, v3
	s_nop 3
	s_cmp_lt_u32 s9, 6
	s_cbranch_scc1 .Lfs_topspin_7

.Lfs_topspin_8:
	s_sleep 3
	global_load_dword v3, v1, s[8:9] sc1
	s_waitcnt vmcnt(0)
	v_readfirstlane_b32 s11, v3
	s_nop 3
	s_cmp_lt_u32 s11, 7
	s_cbranch_scc1 .Lfs_topspin_8

.Lfs_topspin_9:
	s_sleep 3
	global_load_dword v3, v1, s[8:9] sc1
	s_waitcnt vmcnt(0)
	v_readfirstlane_b32 s11, v3
	s_nop 3
	s_cmp_lt_u32 s11, 8
	s_cbranch_scc1 .Lfs_topspin_9

.Lfs_topspin_10:
	s_sleep 3
	global_load_dword v3, v1, s[6:7] sc1
	s_waitcnt vmcnt(0)
	v_readfirstlane_b32 s9, v3
	s_nop 3
	s_cmp_lt_u32 s9, 9
	s_cbranch_scc1 .Lfs_topspin_10
